# spatial phase: extra ctx chunks beyond one round split into 8 group units over 32 blocks
# speedup vs baseline: 1.0121x; 1.0011x over previous
.LBB0_171:
	s_mul_i32 s5, s60, 0x58
	s_getpc_b64 s[0:1]
	s_add_u32 s0, s0, g_phases@rel32@lo+4
	s_addc_u32 s1, s1, g_phases@rel32@hi+12
	s_mul_hi_i32 s3, s60, 0x58
	s_add_u32 s0, s0, s5
	s_addc_u32 s1, s1, s3
	v_writelane_b32 v250, s0, 39
	s_waitcnt lgkmcnt(0)
	s_load_dwordx2 s[20:21], s[0:1], 0x0
	s_mov_b64 s[6:7], -1
	v_writelane_b32 v250, s1, 40
	s_waitcnt lgkmcnt(0)
	s_cmp_lt_i32 s20, 4
	s_cbranch_scc1 .LBB0_195
	s_cmp_lt_i32 s20, 5
	s_cbranch_scc1 .LBB0_192
	s_cmp_lt_i32 s20, 6
	s_cbranch_scc1 .LBB0_186
	s_cmp_eq_u32 s20, 6
	s_cbranch_scc0 .LBB0_185
	v_readlane_b32 s0, v250, 39
	v_readlane_b32 s1, v250, 40
	s_load_dword s0, s[0:1], 0x1c
	v_mov_b32_e32 v0, v168
	s_waitcnt lgkmcnt(0)
	s_ashr_i32 s1, s0, 31
	s_lshr_b32 s1, s1, 25
	s_add_i32 s0, s0, s1
	s_ashr_i32 s5, s0, 7
	s_cmp_ge_i32 s84, s5
	s_cbranch_scc1 .LBB0_185
	s_movk_i32 s100, 0x1000
	s_mov_b32 s101, 0
	v_ashrrev_i32_e32 v6, 2, v0
	s_movk_i32 s12, 0x110
	v_lshlrev_b32_e32 v5, 6, v0
	v_mul_lo_u32 v4, v6, s12
	v_and_b32_e32 v5, 0xc0, v5
	s_movk_i32 s3, 0x100
	v_and_b32_e32 v11, 0x7f, v0
	v_add3_u32 v84, s3, v4, v5
	v_lshlrev_b32_e32 v8, 2, v11
	v_readlane_b32 s3, v250, 8
	v_and_b32_e32 v10, -16, v6
	v_lshlrev_b32_e32 v2, 7, v6
	v_add_u32_e32 v85, s3, v8
	v_readlane_b32 s3, v250, 3
	v_and_b32_e32 v4, 0xffffffe0, v6
	v_and_b32_e32 v7, 15, v0
	v_add_u32_e32 v86, s3, v8
	v_bfi_b32 v8, -16, v6, v0
	v_and_b32_e32 v6, 48, v0
	v_add_u32_e32 v6, 0x100, v6
	v_mad_u64_u32 v[32:33], s[10:11], v8, s12, v[6:7]
	v_lshrrev_b32_e32 v8, 2, v0
	v_and_b32_e32 v13, 12, v8
	v_ashrrev_i32_e32 v8, 3, v4
	v_or_b32_e32 v9, 16, v8
	v_mul_lo_u32 v15, v9, s12
	v_or_b32_e32 v9, 32, v8
	v_mul_lo_u32 v16, v9, s12
	v_or_b32_e32 v9, 48, v8
	v_mul_lo_u32 v17, v9, s12
	v_or_b32_e32 v9, 64, v8
	v_mul_lo_u32 v18, v9, s12
	v_or_b32_e32 v9, 0x50, v8
	v_mul_lo_u32 v19, v9, s12
	v_or_b32_e32 v9, 0x60, v8
	v_mul_lo_u32 v20, v9, s12
	v_or_b32_e32 v9, 0x70, v8
	v_mul_lo_u32 v21, v9, s12
	v_or_b32_e32 v9, 17, v8
	v_mul_lo_u32 v22, v9, s12
	v_or_b32_e32 v9, 33, v8
	v_mul_lo_u32 v23, v9, s12
	v_or_b32_e32 v9, 49, v8
	v_mul_lo_u32 v24, v9, s12
	v_or_b32_e32 v9, 0x41, v8
	v_mul_lo_u32 v25, v9, s12
	v_or_b32_e32 v9, 0x51, v8
	v_mul_lo_u32 v26, v9, s12
	v_or_b32_e32 v9, 0x61, v8
	v_mul_lo_u32 v27, v9, s12
	v_or_b32_e32 v9, 0x71, v8
	v_mul_lo_u32 v28, v9, s12
	v_or_b32_e32 v9, 18, v8
	v_mul_lo_u32 v29, v9, s12
	v_or_b32_e32 v9, 34, v8
	v_mul_lo_u32 v30, v9, s12
	v_or_b32_e32 v9, 50, v8
	v_mul_lo_u32 v31, v9, s12
	v_or_b32_e32 v9, 0x42, v8
	v_mul_lo_u32 v41, v9, s12
	v_or_b32_e32 v9, 0x52, v8
	v_mul_lo_u32 v14, v8, s12
	v_mul_lo_u32 v49, v9, s12
	v_or_b32_e32 v9, 0x62, v8
	v_or_b32_e32 v8, 0x72, v8
	s_ashr_i32 s0, s21, 1
	v_mul_lo_u32 v53, v8, s12
	v_ashrrev_i32_e32 v8, 5, v0
	v_readlane_b32 s68, v252, 34
	s_lshl_b32 s8, s0, 10
	v_mul_lo_u32 v51, v9, s12
	v_or_b32_e32 v9, 3, v8
	v_readlane_b32 s69, v252, 35
	v_readlane_b32 s70, v252, 36
	v_readlane_b32 s71, v252, 37
	v_readlane_b32 s72, v252, 38
	v_readlane_b32 s73, v252, 39
	s_ashr_i32 s1, s0, 31
	s_ashr_i32 s9, s8, 31
	v_mul_lo_u32 v57, v9, s12
	v_or_b32_e32 v9, 19, v8
	v_readlane_b32 s74, v252, 40
	v_readlane_b32 s75, v252, 41
	v_readlane_b32 s76, v252, 42
	v_readlane_b32 s77, v252, 43
	s_mov_b64 s[68:69], s[72:73]
	s_lshl_b64 s[6:7], s[0:1], 18
	s_lshl_b64 s[0:1], s[0:1], 12
	v_mul_lo_u32 v59, v9, s12
	v_or_b32_e32 v9, 35, v8
	s_lshl_b64 s[8:9], s[8:9], 2
	s_mov_b64 s[70:71], s[74:75]
	v_mul_lo_u32 v60, v9, s12
	v_or_b32_e32 v9, 51, v8
	s_add_u32 s10, s70, s8
	v_mul_lo_u32 v61, v9, s12
	v_or_b32_e32 v9, 0x43, v8
	s_mov_b64 s[72:73], s[76:77]
	s_addc_u32 s11, s71, s9
	v_and_b32_e32 v1, 63, v0
	v_mul_lo_u32 v62, v9, s12
	v_or_b32_e32 v9, 0x53, v8
	s_add_u32 s8, s72, s8
	v_readlane_b32 s2, v250, 19
	v_ashrrev_i32_e32 v5, 31, v4
	v_mul_lo_u32 v63, v9, s12
	v_or_b32_e32 v9, 0x63, v8
	v_or_b32_e32 v8, 0x73, v8
	s_addc_u32 s9, s73, s9
	v_lshlrev_b32_e32 v170, 5, v1
	v_readlane_b32 s3, v250, 20
	v_mul_lo_u32 v64, v9, s12
	v_mul_lo_u32 v65, v8, s12
	v_lshlrev_b64 v[8:9], 2, v[4:5]
	v_lshl_add_u64 v[38:39], s[2:3], 0, v[170:171]
	s_add_u32 s3, s6, 0x5e00020
	v_readlane_b32 s80, v252, 46
	v_readlane_b32 s81, v252, 47
	v_lshl_add_u64 v[34:35], s[10:11], 0, v[8:9]
	v_lshl_add_u64 v[36:37], s[8:9], 0, v[8:9]
	v_and_b32_e32 v8, 0xffffffc0, v0
	s_addc_u32 s6, s7, 0
	v_and_b32_e32 v0, 3, v0
	v_cmp_eq_u32_e32 vcc, 0, v1
	v_ashrrev_i32_e32 v3, 31, v2
	s_mov_b64 s[76:77], s[80:81]
	v_lshl_or_b32 v0, v0, 6, s3
	v_mov_b32_e32 v1, s6
	v_lshl_add_u64 v[42:43], v[2:3], 1, v[0:1]
	v_or_b32_e32 v0, v10, v13
	s_add_u32 s0, s76, s0
	v_ashrrev_i32_e32 v1, 31, v0
	s_addc_u32 s1, s77, s1
	v_lshl_add_u64 v[44:45], v[0:1], 2, s[0:1]
	v_readlane_b32 s0, v251, 61
	v_readlane_b32 s8, v251, 63
	v_lshl_add_u32 v12, v11, 1, v192
	v_add_u32_e32 v50, s0, v0
	v_readlane_b32 s0, v251, 62
	v_mul_u32_u24_e32 v66, 0x110, v7
	v_add_u32_e32 v40, s8, v10
	v_lshlrev_b32_e32 v1, 4, v7
	v_add_u32_e32 v52, s0, v0
	v_readlane_b32 s0, v250, 0
	v_add_u32_e32 v33, 0x100, v8
	v_lshlrev_b64 v[46:47], 1, v[4:5]
	v_add_u32_e32 v48, s8, v11
	v_or_b32_e32 v170, 0x164d0000, v1
	v_or_b32_e32 v54, 0xa1d0000, v1
	v_mov_b32_e32 v55, v171
	v_add_u32_e32 v56, v40, v13
	v_add_u32_e32 v58, s0, v0
	v_add_u32_e32 v87, v12, v14
	v_add_u32_e32 v88, v12, v15
	v_add_u32_e32 v89, v12, v16
	v_add_u32_e32 v90, v12, v17
	v_add_u32_e32 v91, v12, v18
	v_add_u32_e32 v92, v12, v19
	v_add_u32_e32 v93, v12, v20
	v_add_u32_e32 v94, v12, v21
	v_add_u32_e32 v95, v12, v22
	v_add_u32_e32 v96, v12, v23
	v_add_u32_e32 v97, v12, v24
	v_add_u32_e32 v98, v12, v25
	v_add_u32_e32 v99, v12, v26
	v_add_u32_e32 v100, v12, v27
	v_add_u32_e32 v101, v12, v28
	v_add_u32_e32 v102, v12, v29
	v_add_u32_e32 v103, v12, v30
	v_add_u32_e32 v104, v12, v31
	v_add_u32_e32 v105, v12, v41
	v_add_u32_e32 v106, v12, v49
	v_add_u32_e32 v107, v12, v51
	v_add_u32_e32 v108, v12, v53
	v_add_u32_e32 v109, v12, v57
	v_add_u32_e32 v110, v12, v59
	v_add_u32_e32 v111, v12, v60
	v_add_u32_e32 v112, v12, v61
	v_add_u32_e32 v113, v12, v62
	v_add_u32_e32 v114, v12, v63
	v_add_u32_e32 v115, v12, v64
	v_add_u32_e32 v116, v12, v65
	v_add_u32_e32 v117, v6, v66
	s_mov_b32 s8, s84
	v_readlane_b32 s3, v251, 60
	v_readlane_b32 s78, v252, 44
	v_readlane_b32 s79, v252, 45
	v_readlane_b32 s82, v252, 48
	v_readlane_b32 s83, v252, 49

.LBB0_181:
	v_ashrrev_i32_e32 v49, 31, v48
	v_lshlrev_b64 v[0:1], 12, v[48:49]
	v_ashrrev_i32_e32 v51, 31, v50
	v_lshl_add_u64 v[60:61], v[46:47], 0, v[0:1]
	v_lshlrev_b64 v[0:1], 11, v[50:51]
	v_ashrrev_i32_e32 v53, 31, v52
	v_lshl_add_u64 v[62:63], v[170:171], 0, v[0:1]
	v_lshlrev_b64 v[0:1], 11, v[52:53]
	v_ashrrev_i32_e32 v57, 31, v56
	v_lshl_add_u64 v[64:65], v[170:171], 0, v[0:1]
	v_lshlrev_b64 v[0:1], 12, v[56:57]
	v_ashrrev_i32_e32 v59, 31, v58
	v_lshl_add_u64 v[66:67], v[54:55], 0, v[0:1]
	v_lshlrev_b64 v[0:1], 12, v[58:59]
	v_lshl_add_u64 v[68:69], v[54:55], 0, v[0:1]
	v_lshlrev_b64 v[0:1], 12, v[52:53]
	v_lshl_add_u64 v[70:71], v[54:55], 0, v[0:1]
	v_lshlrev_b64 v[0:1], 12, v[50:51]
	v_lshl_add_u64 v[72:73], v[54:55], 0, v[0:1]
	v_lshlrev_b64 v[0:1], 11, v[56:57]
	v_lshl_add_u64 v[74:75], v[170:171], 0, v[0:1]
	v_lshlrev_b64 v[0:1], 11, v[58:59]
	v_lshl_add_u64 v[76:77], v[170:171], 0, v[0:1]
	s_mov_b64 s[6:7], 0
	v_mov_b64_e32 v[78:79], v[42:43]
	s_cmp_eq_u32 s101, 0
	s_cbranch_scc1 .Lsp_nooff
	s_and_b32 s0, s84, 7
	s_lshl_b32 s6, s0, 9
	s_add_i32 s100, s6, 0x200
	s_lshl_b32 s1, s0, 8
	v_mov_b32_e32 v254, s1
	v_mov_b32_e32 v255, 0
	v_lshl_add_u64 v[60:61], v[60:61], 0, v[254:255]
	v_lshl_add_u64 v[62:63], v[62:63], 0, v[254:255]
	v_lshl_add_u64 v[64:65], v[64:65], 0, v[254:255]
	v_lshl_add_u64 v[66:67], v[66:67], 0, v[254:255]
	v_lshl_add_u64 v[68:69], v[68:69], 0, v[254:255]
	v_lshl_add_u64 v[70:71], v[70:71], 0, v[254:255]
	v_lshl_add_u64 v[72:73], v[72:73], 0, v[254:255]
	v_lshl_add_u64 v[74:75], v[74:75], 0, v[254:255]
	v_lshl_add_u64 v[76:77], v[76:77], 0, v[254:255]
	s_lshl_b32 s1, s0, 15
	v_mov_b32_e32 v254, s1
	v_lshl_add_u64 v[78:79], v[78:79], 0, v[254:255]
.Lsp_nooff:
.LBB0_182:
	v_lshl_add_u64 v[12:13], s[26:27], 0, v[78:79]
	s_waitcnt lgkmcnt(0)
	s_barrier
	global_load_dwordx4 v[0:3], v[12:13], off offset:16
	global_load_dwordx4 v[4:7], v[12:13], off
	global_load_dwordx4 v[8:11], v[12:13], off offset:-16
	s_nop 0
	global_load_dwordx4 v[12:15], v[12:13], off offset:-32
	s_mov_b64 s[0:1], 0xa1d0800
	v_lshl_add_u64 v[16:17], v[36:37], 0, s[6:7]
	s_waitcnt vmcnt(0)
	ds_write_b128 v84, v[12:15]
	ds_write_b128 v84, v[8:11] offset:16
	ds_write_b128 v84, v[4:7] offset:32
	ds_write_b128 v84, v[0:3] offset:48
	v_lshl_add_u64 v[0:1], s[26:27], 0, v[60:61]
	v_lshl_add_u64 v[10:11], v[0:1], 0, s[0:1]
	s_mov_b32 s0, 0xa1d0000
	v_add_co_u32_e64 v0, s[40:41], s0, v0
	v_lshl_add_u64 v[4:5], v[34:35], 0, s[6:7]
	s_nop 0
	v_addc_co_u32_e64 v1, s[40:41], 0, v1, s[40:41]
	ds_read_b32 v19, v85
	ds_read_b32 v18, v86
	global_load_dwordx4 v[6:9], v[0:1], off offset:2048
	s_nop 0
	global_load_dwordx4 v[0:3], v[10:11], off offset:48
	global_load_dwordx4 v[12:15], v[10:11], off offset:32
	global_load_dwordx4 v[20:23], v[10:11], off offset:16
	global_load_dwordx4 v[24:27], v[4:5], off offset:48
	global_load_dwordx4 v[28:31], v[4:5], off offset:32
	global_load_dwordx4 v[80:83], v[4:5], off offset:16
	global_load_dwordx4 v[118:121], v[4:5], off
	global_load_dwordx4 v[122:125], v[16:17], off offset:48
	global_load_dwordx4 v[126:129], v[16:17], off offset:32
	global_load_dwordx4 v[130:133], v[16:17], off offset:16
	global_load_dwordx4 v[134:137], v[16:17], off
	v_lshl_add_u64 v[60:61], v[60:61], 0, s[66:67]
	s_waitcnt vmcnt(11)
	v_lshlrev_b32_e32 v10, 16, v6
	v_and_b32_e32 v6, 0xffff0000, v6
	s_waitcnt lgkmcnt(1)
	v_sub_f32_e32 v10, v10, v19
	v_sub_f32_e32 v6, v6, v19
	s_waitcnt lgkmcnt(0)
	v_mul_f32_e32 v10, v18, v10
	v_mul_f32_e32 v6, v18, v6
	s_waitcnt vmcnt(0)
	v_fma_f32 v10, v118, v10, v134
	v_fma_f32 v6, v119, v6, v135
	v_cvt_pk_bf16_f32 v10, v10, s0
	v_cvt_pk_bf16_f32 v6, v6, s0
	ds_write_b16 v87, v10 offset:34816
	ds_write_b16 v88, v6 offset:34816
	v_lshlrev_b32_e32 v6, 16, v7
	v_sub_f32_e32 v6, v6, v19
	v_and_b32_e32 v7, 0xffff0000, v7
	v_mul_f32_e32 v6, v18, v6
	v_sub_f32_e32 v7, v7, v19
	v_fma_f32 v6, v6, v120, v136
	v_mul_f32_e32 v7, v18, v7
	v_fmac_f32_e32 v137, v7, v121
	v_cvt_pk_bf16_f32 v6, v6, s0
	ds_write_b16 v89, v6 offset:34816
	v_cvt_pk_bf16_f32 v6, v137, s0
	ds_write_b16 v90, v6 offset:34816
	v_lshlrev_b32_e32 v6, 16, v8
	v_sub_f32_e32 v6, v6, v19
	v_and_b32_e32 v7, 0xffff0000, v8
	v_mul_f32_e32 v6, v18, v6
	v_sub_f32_e32 v7, v7, v19
	v_fma_f32 v6, v6, v80, v130
	v_mul_f32_e32 v7, v18, v7
	v_fma_f32 v7, v7, v81, v131
	v_cvt_pk_bf16_f32 v6, v6, s0
	ds_write_b16 v91, v6 offset:34816
	v_cvt_pk_bf16_f32 v6, v7, s0
	ds_write_b16 v92, v6 offset:34816
	v_lshlrev_b32_e32 v6, 16, v9
	v_sub_f32_e32 v6, v6, v19
	v_and_b32_e32 v7, 0xffff0000, v9
	v_mul_f32_e32 v6, v18, v6
	v_sub_f32_e32 v7, v7, v19
	v_fma_f32 v6, v6, v82, v132
	v_mul_f32_e32 v7, v18, v7
	v_fmac_f32_e32 v133, v7, v83
	v_cvt_pk_bf16_f32 v6, v6, s0
	ds_write_b16 v93, v6 offset:34816
	v_cvt_pk_bf16_f32 v6, v133, s0
	ds_write_b16 v94, v6 offset:34816
	v_lshlrev_b32_e32 v6, 16, v20
	v_sub_f32_e32 v6, v6, v19
	v_and_b32_e32 v7, 0xffff0000, v20
	v_mul_f32_e32 v6, v18, v6
	v_sub_f32_e32 v7, v7, v19
	v_fma_f32 v6, v28, v6, v126
	v_mul_f32_e32 v7, v18, v7
	v_fma_f32 v7, v29, v7, v127
	v_cvt_pk_bf16_f32 v6, v6, s0
	ds_write_b16 v87, v6 offset:35088
	v_cvt_pk_bf16_f32 v6, v7, s0
	ds_write_b16 v95, v6 offset:34816
	v_lshlrev_b32_e32 v6, 16, v21
	v_sub_f32_e32 v6, v6, v19
	v_and_b32_e32 v7, 0xffff0000, v21
	v_mul_f32_e32 v6, v18, v6
	v_sub_f32_e32 v7, v7, v19
	v_fma_f32 v6, v6, v30, v128
	v_mul_f32_e32 v7, v18, v7
	v_fmac_f32_e32 v129, v7, v31
	v_cvt_pk_bf16_f32 v6, v6, s0
	ds_write_b16 v96, v6 offset:34816
	v_cvt_pk_bf16_f32 v6, v129, s0
	ds_write_b16 v97, v6 offset:34816
	v_lshlrev_b32_e32 v6, 16, v22
	v_sub_f32_e32 v6, v6, v19
	v_and_b32_e32 v7, 0xffff0000, v22
	v_mul_f32_e32 v6, v18, v6
	v_sub_f32_e32 v7, v7, v19
	v_fma_f32 v6, v6, v24, v122
	v_mul_f32_e32 v7, v18, v7
	v_fma_f32 v7, v7, v25, v123
	v_cvt_pk_bf16_f32 v6, v6, s0
	ds_write_b16 v98, v6 offset:34816
	v_cvt_pk_bf16_f32 v6, v7, s0
	ds_write_b16 v99, v6 offset:34816
	v_lshlrev_b32_e32 v6, 16, v23
	v_sub_f32_e32 v6, v6, v19
	v_and_b32_e32 v7, 0xffff0000, v23
	v_mul_f32_e32 v6, v18, v6
	v_sub_f32_e32 v7, v7, v19
	v_fma_f32 v6, v6, v26, v124
	v_mul_f32_e32 v7, v18, v7
	v_fmac_f32_e32 v125, v7, v27
	v_cvt_pk_bf16_f32 v6, v6, s0
	ds_write_b16 v100, v6 offset:34816
	v_cvt_pk_bf16_f32 v6, v125, s0
	ds_write_b16 v101, v6 offset:34816
	v_lshlrev_b32_e32 v6, 16, v12
	v_sub_f32_e32 v6, v6, v19
	v_mul_f32_e32 v41, v18, v6
	global_load_dwordx4 v[8:11], v[4:5], off offset:112
	global_load_dwordx4 v[20:23], v[4:5], off offset:96
	global_load_dwordx4 v[24:27], v[4:5], off offset:80
	global_load_dwordx4 v[28:31], v[4:5], off offset:64
	s_nop 0
	global_load_dwordx4 v[4:7], v[16:17], off offset:112
	global_load_dwordx4 v[80:83], v[16:17], off offset:96
	global_load_dwordx4 v[118:121], v[16:17], off offset:80
	global_load_dwordx4 v[122:125], v[16:17], off offset:64
	v_and_b32_e32 v12, 0xffff0000, v12
	v_sub_f32_e32 v12, v12, v19
	v_mul_f32_e32 v12, v18, v12
	s_waitcnt vmcnt(0)
	v_fma_f32 v16, v28, v41, v122
	v_fma_f32 v12, v29, v12, v123
	v_cvt_pk_bf16_f32 v16, v16, s0
	v_cvt_pk_bf16_f32 v12, v12, s0
	ds_write_b16 v87, v16 offset:35360
	ds_write_b16 v102, v12 offset:34816
	v_lshlrev_b32_e32 v12, 16, v13
	v_sub_f32_e32 v12, v12, v19
	v_and_b32_e32 v13, 0xffff0000, v13
	v_mul_f32_e32 v12, v18, v12
	v_sub_f32_e32 v13, v13, v19
	v_fma_f32 v12, v12, v30, v124
	v_mul_f32_e32 v13, v18, v13
	v_fmac_f32_e32 v125, v13, v31
	v_cvt_pk_bf16_f32 v12, v12, s0
	ds_write_b16 v103, v12 offset:34816
	v_cvt_pk_bf16_f32 v12, v125, s0
	ds_write_b16 v104, v12 offset:34816
	v_lshlrev_b32_e32 v12, 16, v14
	v_sub_f32_e32 v12, v12, v19
	v_and_b32_e32 v13, 0xffff0000, v14
	v_mul_f32_e32 v12, v18, v12
	v_sub_f32_e32 v13, v13, v19
	v_fma_f32 v12, v12, v24, v118
	v_mul_f32_e32 v13, v18, v13
	v_fma_f32 v13, v13, v25, v119
	v_cvt_pk_bf16_f32 v12, v12, s0
	ds_write_b16 v105, v12 offset:34816
	v_cvt_pk_bf16_f32 v12, v13, s0
	ds_write_b16 v106, v12 offset:34816
	v_lshlrev_b32_e32 v12, 16, v15
	v_sub_f32_e32 v12, v12, v19
	v_and_b32_e32 v13, 0xffff0000, v15
	v_mul_f32_e32 v12, v18, v12
	v_sub_f32_e32 v13, v13, v19
	v_fma_f32 v12, v12, v26, v120
	v_mul_f32_e32 v13, v18, v13
	v_fmac_f32_e32 v121, v13, v27
	v_cvt_pk_bf16_f32 v12, v12, s0
	ds_write_b16 v107, v12 offset:34816
	v_cvt_pk_bf16_f32 v12, v121, s0
	ds_write_b16 v108, v12 offset:34816
	v_lshlrev_b32_e32 v12, 16, v0
	v_and_b32_e32 v0, 0xffff0000, v0
	v_sub_f32_e32 v12, v12, v19
	v_sub_f32_e32 v0, v0, v19
	v_mul_f32_e32 v12, v18, v12
	v_mul_f32_e32 v0, v18, v0
	v_fma_f32 v12, v20, v12, v80
	v_fma_f32 v0, v21, v0, v81
	v_cvt_pk_bf16_f32 v12, v12, s0
	v_cvt_pk_bf16_f32 v0, v0, s0
	ds_write_b16 v109, v12 offset:34816
	ds_write_b16 v110, v0 offset:34816
	v_lshlrev_b32_e32 v0, 16, v1
	v_sub_f32_e32 v0, v0, v19
	v_and_b32_e32 v1, 0xffff0000, v1
	v_mul_f32_e32 v0, v18, v0
	v_sub_f32_e32 v1, v1, v19
	v_fma_f32 v0, v0, v22, v82
	v_mul_f32_e32 v1, v18, v1
	v_fmac_f32_e32 v83, v1, v23
	v_cvt_pk_bf16_f32 v0, v0, s0
	ds_write_b16 v111, v0 offset:34816
	v_cvt_pk_bf16_f32 v0, v83, s0
	ds_write_b16 v112, v0 offset:34816
	v_lshlrev_b32_e32 v0, 16, v2
	v_sub_f32_e32 v0, v0, v19
	v_and_b32_e32 v1, 0xffff0000, v2
	v_mul_f32_e32 v0, v18, v0
	v_sub_f32_e32 v1, v1, v19
	v_fma_f32 v0, v0, v8, v4
	v_mul_f32_e32 v1, v18, v1
	v_fma_f32 v1, v1, v9, v5
	v_cvt_pk_bf16_f32 v0, v0, s0
	ds_write_b16 v113, v0 offset:34816
	v_cvt_pk_bf16_f32 v0, v1, s0
	ds_write_b16 v114, v0 offset:34816
	v_lshlrev_b32_e32 v0, 16, v3
	v_sub_f32_e32 v0, v0, v19
	v_and_b32_e32 v1, 0xffff0000, v3
	v_mul_f32_e32 v0, v18, v0
	v_sub_f32_e32 v1, v1, v19
	v_fma_f32 v0, v0, v10, v6
	v_mul_f32_e32 v1, v18, v1
	v_fmac_f32_e32 v7, v1, v11
	v_cvt_pk_bf16_f32 v0, v0, s0
	ds_write_b16 v115, v0 offset:34816
	v_cvt_pk_bf16_f32 v0, v7, s0
	ds_write_b16 v116, v0 offset:34816
	s_waitcnt lgkmcnt(0)
	s_barrier
	ds_read_b128 v[0:3], v32
	ds_read_b128 v[4:7], v117 offset:34816
	ds_read_b128 v[8:11], v117 offset:39168
	ds_read_b128 v[12:15], v117 offset:43520
	ds_read_b128 v[16:19], v117 offset:47872
	ds_read_b128 v[20:23], v117 offset:52224
	ds_read_b128 v[24:27], v117 offset:56576
	ds_read_b128 v[28:31], v117 offset:60928
	ds_read_b128 v[80:83], v117 offset:65280
	s_waitcnt lgkmcnt(7)
	v_mfma_f32_16x16x32_bf16 v[4:7], v[0:3], v[4:7], 0
	s_mov_b64 s[0:1], 0x8000
	v_lshl_add_u64 v[78:79], v[78:79], 0, s[0:1]
	s_waitcnt lgkmcnt(6)
	v_mfma_f32_16x16x32_bf16 v[8:11], v[0:3], v[8:11], 0
	s_waitcnt lgkmcnt(5)
	v_mfma_f32_16x16x32_bf16 v[12:15], v[0:3], v[12:15], 0
	s_waitcnt lgkmcnt(4)
	v_mfma_f32_16x16x32_bf16 v[16:19], v[0:3], v[16:19], 0
	s_waitcnt lgkmcnt(3)
	v_mfma_f32_16x16x32_bf16 v[20:23], v[0:3], v[20:23], 0
	s_waitcnt lgkmcnt(2)
	v_mfma_f32_16x16x32_bf16 v[24:27], v[0:3], v[24:27], 0
	s_waitcnt lgkmcnt(1)
	v_mfma_f32_16x16x32_bf16 v[28:31], v[0:3], v[28:31], 0
	s_waitcnt lgkmcnt(0)
	v_mfma_f32_16x16x32_bf16 v[0:3], v[0:3], v[80:83], 0
	ds_read_b128 v[80:83], v32 offset:64
	ds_read_b128 v[118:121], v117 offset:34880
	s_waitcnt lgkmcnt(0)
	v_mfma_f32_16x16x32_bf16 v[4:7], v[80:83], v[118:121], v[4:7]
	ds_read_b128 v[118:121], v117 offset:39232
	s_waitcnt lgkmcnt(0)
	v_mfma_f32_16x16x32_bf16 v[8:11], v[80:83], v[118:121], v[8:11]
	ds_read_b128 v[118:121], v117 offset:43584
	s_waitcnt lgkmcnt(0)
	v_mfma_f32_16x16x32_bf16 v[12:15], v[80:83], v[118:121], v[12:15]
	ds_read_b128 v[118:121], v117 offset:47936
	s_waitcnt lgkmcnt(0)
	v_mfma_f32_16x16x32_bf16 v[16:19], v[80:83], v[118:121], v[16:19]
	ds_read_b128 v[118:121], v117 offset:52288
	s_waitcnt lgkmcnt(0)
	v_mfma_f32_16x16x32_bf16 v[20:23], v[80:83], v[118:121], v[20:23]
	ds_read_b128 v[118:121], v117 offset:56640
	s_waitcnt lgkmcnt(0)
	v_mfma_f32_16x16x32_bf16 v[24:27], v[80:83], v[118:121], v[24:27]
	ds_read_b128 v[118:121], v117 offset:60992
	s_waitcnt lgkmcnt(0)
	v_mfma_f32_16x16x32_bf16 v[28:31], v[80:83], v[118:121], v[28:31]
	ds_read_b128 v[118:121], v117 offset:65344
	s_waitcnt lgkmcnt(0)
	v_mfma_f32_16x16x32_bf16 v[0:3], v[80:83], v[118:121], v[0:3]
	ds_read_b128 v[80:83], v32 offset:128
	ds_read_b128 v[118:121], v117 offset:34944
	s_waitcnt lgkmcnt(0)
	v_mfma_f32_16x16x32_bf16 v[4:7], v[80:83], v[118:121], v[4:7]
	ds_read_b128 v[118:121], v117 offset:39296
	s_waitcnt lgkmcnt(0)
	v_mfma_f32_16x16x32_bf16 v[8:11], v[80:83], v[118:121], v[8:11]
	ds_read_b128 v[118:121], v117 offset:43648
	s_waitcnt lgkmcnt(0)
	v_mfma_f32_16x16x32_bf16 v[12:15], v[80:83], v[118:121], v[12:15]
	ds_read_b128 v[118:121], v117 offset:48000
	s_waitcnt lgkmcnt(0)
	v_mfma_f32_16x16x32_bf16 v[16:19], v[80:83], v[118:121], v[16:19]
	ds_read_b128 v[118:121], v117 offset:52352
	s_waitcnt lgkmcnt(0)
	v_mfma_f32_16x16x32_bf16 v[20:23], v[80:83], v[118:121], v[20:23]
	ds_read_b128 v[118:121], v117 offset:56704
	s_waitcnt lgkmcnt(0)
	v_mfma_f32_16x16x32_bf16 v[24:27], v[80:83], v[118:121], v[24:27]
	ds_read_b128 v[118:121], v117 offset:61056
	s_waitcnt lgkmcnt(0)
	v_mfma_f32_16x16x32_bf16 v[28:31], v[80:83], v[118:121], v[28:31]
	ds_read_b128 v[118:121], v117 offset:65408
	s_waitcnt lgkmcnt(0)
	v_mfma_f32_16x16x32_bf16 v[80:83], v[80:83], v[118:121], v[0:3]
	ds_read_b128 v[118:121], v32 offset:192
	s_nop 1
	ds_read_b128 v[0:3], v117 offset:35008
	s_waitcnt lgkmcnt(0)
	v_mfma_f32_16x16x32_bf16 v[0:3], v[118:121], v[0:3], v[4:7]
	s_nop 2
	ds_read_b128 v[4:7], v117 offset:39360
	s_waitcnt lgkmcnt(0)
	v_mfma_f32_16x16x32_bf16 v[4:7], v[118:121], v[4:7], v[8:11]
	s_nop 2
	ds_read_b128 v[8:11], v117 offset:43712
	s_waitcnt lgkmcnt(0)
	v_mfma_f32_16x16x32_bf16 v[8:11], v[118:121], v[8:11], v[12:15]
	s_nop 2
	ds_read_b128 v[12:15], v117 offset:48064
	s_waitcnt lgkmcnt(0)
	v_mfma_f32_16x16x32_bf16 v[12:15], v[118:121], v[12:15], v[16:19]
	s_nop 2
	ds_read_b128 v[16:19], v117 offset:52416
	s_waitcnt lgkmcnt(0)
	v_mfma_f32_16x16x32_bf16 v[16:19], v[118:121], v[16:19], v[20:23]
	s_nop 2
	ds_read_b128 v[20:23], v117 offset:56768
	s_waitcnt lgkmcnt(0)
	v_mfma_f32_16x16x32_bf16 v[20:23], v[118:121], v[20:23], v[24:27]
	s_nop 2
	ds_read_b128 v[24:27], v117 offset:61120
	s_waitcnt lgkmcnt(0)
	v_mfma_f32_16x16x32_bf16 v[24:27], v[118:121], v[24:27], v[28:31]
	s_nop 2
	ds_read_b128 v[28:31], v117 offset:65472
	s_waitcnt lgkmcnt(0)
	v_mfma_f32_16x16x32_bf16 v[28:31], v[118:121], v[28:31], v[80:83]
	s_nop 2
	v_lshl_add_u64 v[80:81], v[44:45], 0, s[6:7]
	v_lshl_add_u64 v[82:83], s[26:27], 0, v[66:67]
	global_load_dword v41, v[80:81], off
	global_load_dwordx4 v[118:121], v[82:83], off
	v_lshl_add_u64 v[82:83], s[26:27], 0, v[74:75]
	s_add_u32 s6, s6, 0x200
	s_addc_u32 s7, s7, 0
	v_lshl_add_u64 v[66:67], v[66:67], 0, s[66:67]
	v_lshl_add_u64 v[74:75], v[74:75], 0, s[66:67]
	s_cmp_eq_u32 s6, s100
	s_waitcnt vmcnt(1)
	v_add_f32_e32 v0, v0, v41
	s_waitcnt vmcnt(0)
	v_lshlrev_b32_e32 v49, 16, v118
	v_mul_f32_e32 v0, v0, v49
	v_and_b32_e32 v49, 0xffff0000, v118
	v_add_f32_e32 v4, v4, v41
	v_mul_f32_e32 v4, v4, v49
	v_cvt_pk_bf16_f32 v118, v0, v4
	v_lshlrev_b32_e32 v0, 16, v119
	v_add_f32_e32 v4, v8, v41
	v_mul_f32_e32 v0, v4, v0
	v_and_b32_e32 v4, 0xffff0000, v119
	v_add_f32_e32 v8, v12, v41
	v_mul_f32_e32 v4, v8, v4
	v_cvt_pk_bf16_f32 v119, v0, v4
	v_lshlrev_b32_e32 v0, 16, v120
	v_add_f32_e32 v4, v16, v41
	v_mul_f32_e32 v0, v4, v0
	v_and_b32_e32 v4, 0xffff0000, v120
	v_add_f32_e32 v8, v20, v41
	v_mul_f32_e32 v4, v8, v4
	v_cvt_pk_bf16_f32 v120, v0, v4
	v_lshlrev_b32_e32 v0, 16, v121
	v_add_f32_e32 v4, v24, v41
	v_mul_f32_e32 v0, v4, v0
	v_and_b32_e32 v4, 0xffff0000, v121
	v_add_f32_e32 v8, v28, v41
	v_mul_f32_e32 v4, v8, v4
	v_cvt_pk_bf16_f32 v121, v0, v4
	global_store_dwordx4 v[82:83], v[118:121], off
	v_lshl_add_u64 v[82:83], s[26:27], 0, v[68:69]
	global_load_dword v0, v[80:81], off offset:4
	global_load_dwordx4 v[118:121], v[82:83], off
	v_lshl_add_u64 v[68:69], v[68:69], 0, s[66:67]
	s_waitcnt vmcnt(1)
	v_add_f32_e32 v1, v1, v0
	s_waitcnt vmcnt(0)
	v_lshlrev_b32_e32 v4, 16, v118
	v_mul_f32_e32 v1, v1, v4
	v_and_b32_e32 v4, 0xffff0000, v118
	v_add_f32_e32 v5, v5, v0
	v_mul_f32_e32 v4, v5, v4
	v_cvt_pk_bf16_f32 v118, v1, v4
	v_lshlrev_b32_e32 v1, 16, v119
	v_add_f32_e32 v4, v9, v0
	v_mul_f32_e32 v1, v4, v1
	v_and_b32_e32 v4, 0xffff0000, v119
	v_add_f32_e32 v5, v13, v0
	v_mul_f32_e32 v4, v5, v4
	v_cvt_pk_bf16_f32 v119, v1, v4
	v_lshlrev_b32_e32 v1, 16, v120
	v_add_f32_e32 v4, v17, v0
	v_mul_f32_e32 v1, v4, v1
	v_and_b32_e32 v4, 0xffff0000, v120
	v_add_f32_e32 v5, v21, v0
	v_mul_f32_e32 v4, v5, v4
	v_cvt_pk_bf16_f32 v120, v1, v4
	v_lshlrev_b32_e32 v1, 16, v121
	v_add_f32_e32 v4, v25, v0
	v_mul_f32_e32 v1, v4, v1
	v_and_b32_e32 v4, 0xffff0000, v121
	v_add_f32_e32 v0, v29, v0
	v_mul_f32_e32 v0, v0, v4
	v_cvt_pk_bf16_f32 v121, v1, v0
	v_lshl_add_u64 v[0:1], s[26:27], 0, v[76:77]
	global_store_dwordx4 v[0:1], v[118:121], off
	v_lshl_add_u64 v[0:1], s[26:27], 0, v[70:71]
	global_load_dword v4, v[80:81], off offset:8
	global_load_dwordx4 v[118:121], v[0:1], off
	v_lshl_add_u64 v[70:71], v[70:71], 0, s[66:67]
	v_lshl_add_u64 v[76:77], v[76:77], 0, s[66:67]
	s_waitcnt vmcnt(1)
	v_add_f32_e32 v1, v2, v4
	s_waitcnt vmcnt(0)
	v_lshlrev_b32_e32 v0, 16, v118
	v_mul_f32_e32 v0, v1, v0
	v_and_b32_e32 v1, 0xffff0000, v118
	v_add_f32_e32 v2, v6, v4
	v_mul_f32_e32 v1, v2, v1
	v_cvt_pk_bf16_f32 v118, v0, v1
	v_lshlrev_b32_e32 v0, 16, v119
	v_add_f32_e32 v1, v10, v4
	v_mul_f32_e32 v0, v1, v0
	v_and_b32_e32 v1, 0xffff0000, v119
	v_add_f32_e32 v2, v14, v4
	v_mul_f32_e32 v1, v2, v1
	v_cvt_pk_bf16_f32 v119, v0, v1
	v_lshlrev_b32_e32 v0, 16, v120
	v_add_f32_e32 v1, v18, v4
	v_mul_f32_e32 v0, v1, v0
	v_and_b32_e32 v1, 0xffff0000, v120
	v_add_f32_e32 v2, v22, v4
	v_mul_f32_e32 v1, v2, v1
	v_cvt_pk_bf16_f32 v120, v0, v1
	v_lshlrev_b32_e32 v0, 16, v121
	v_add_f32_e32 v1, v26, v4
	v_mul_f32_e32 v0, v1, v0
	v_and_b32_e32 v1, 0xffff0000, v121
	v_add_f32_e32 v2, v30, v4
	v_mul_f32_e32 v1, v2, v1
	v_cvt_pk_bf16_f32 v121, v0, v1
	v_lshl_add_u64 v[0:1], s[26:27], 0, v[64:65]
	global_store_dwordx4 v[0:1], v[118:121], off
	v_lshl_add_u64 v[0:1], s[26:27], 0, v[72:73]
	global_load_dword v4, v[80:81], off offset:12
	v_lshl_add_u64 v[64:65], v[64:65], 0, s[66:67]
	global_load_dwordx4 v[80:83], v[0:1], off
	v_lshl_add_u64 v[72:73], v[72:73], 0, s[66:67]
	s_waitcnt vmcnt(1)
	v_add_f32_e32 v1, v3, v4
	v_add_f32_e32 v2, v7, v4
	s_waitcnt vmcnt(0)
	v_lshlrev_b32_e32 v0, 16, v80
	v_mul_f32_e32 v0, v1, v0
	v_and_b32_e32 v1, 0xffff0000, v80
	v_mul_f32_e32 v1, v2, v1
	v_cvt_pk_bf16_f32 v0, v0, v1
	v_lshlrev_b32_e32 v1, 16, v81
	v_add_f32_e32 v2, v11, v4
	v_mul_f32_e32 v1, v2, v1
	v_and_b32_e32 v2, 0xffff0000, v81
	v_add_f32_e32 v3, v15, v4
	v_mul_f32_e32 v2, v3, v2
	v_cvt_pk_bf16_f32 v1, v1, v2
	v_lshlrev_b32_e32 v2, 16, v82
	v_add_f32_e32 v3, v19, v4
	v_mul_f32_e32 v2, v3, v2
	v_and_b32_e32 v3, 0xffff0000, v82
	v_add_f32_e32 v5, v23, v4
	v_mul_f32_e32 v3, v5, v3
	v_cvt_pk_bf16_f32 v2, v2, v3
	v_lshlrev_b32_e32 v3, 16, v83
	v_add_f32_e32 v5, v27, v4
	v_mul_f32_e32 v3, v5, v3
	v_and_b32_e32 v5, 0xffff0000, v83
	v_add_f32_e32 v4, v31, v4
	v_mul_f32_e32 v4, v4, v5
	v_cvt_pk_bf16_f32 v3, v3, v4
	v_lshl_add_u64 v[4:5], s[26:27], 0, v[62:63]
	v_lshl_add_u64 v[62:63], v[62:63], 0, s[66:67]
	global_store_dwordx4 v[4:5], v[0:3], off
	s_cbranch_scc0 .LBB0_182
	s_cmp_eq_u32 s101, 1
	s_cbranch_scc1 .Lsp_last
	s_add_i32 s8, s8, s62
	v_add_u32_e32 v40, s3, v40
	v_add_u32_e32 v48, s3, v48
	v_add_u32_e32 v50, s3, v50
	v_add_u32_e32 v52, s3, v52
	v_add_u32_e32 v56, s3, v56
	v_add_u32_e32 v58, s3, v58
	s_cmp_lg_u32 s62, 0x100
	s_cbranch_scc1 .Lsp_normal
	s_sub_i32 s0, s5, 0x100
	s_cmp_lt_i32 s0, 1
	s_cbranch_scc1 .Lsp_normal
	s_cmp_gt_i32 s0, 32
	s_cbranch_scc1 .Lsp_normal
	s_lshl_b32 s0, s0, 3
	s_cmp_ge_u32 s84, s0
	s_cbranch_scc1 .Lsp_last
	s_mov_b32 s101, 1
	s_lshr_b32 s1, s84, 3
	s_sub_i32 s1, s84, s1
	s_lshl_b32 s1, s1, 7
	v_subrev_u32_e32 v40, s1, v40
	v_subrev_u32_e32 v48, s1, v48
	v_subrev_u32_e32 v50, s1, v50
	v_subrev_u32_e32 v52, s1, v52
	v_subrev_u32_e32 v56, s1, v56
	v_subrev_u32_e32 v58, s1, v58
	s_barrier
	s_branch .LBB0_177
	s_nop 0
	s_nop 0
	s_nop 0
.Lsp_normal:
	s_cmp_ge_i32 s8, s5
	s_barrier
	s_cbranch_scc0 .LBB0_177
	s_branch .Lsp_done

.Lsp_done:
	v_readlane_b32 s76, v250, 16
	v_readlane_b32 s68, v250, 23
	v_readlane_b32 s70, v250, 25
	v_readlane_b32 s80, v250, 27
	v_readlane_b32 s78, v250, 15
	v_readlane_b32 s77, v250, 17
	v_readlane_b32 s74, v250, 18
	v_readlane_b32 s73, v250, 21
	v_readlane_b32 s65, v250, 22
	v_readlane_b32 s69, v250, 24
	v_readlane_b32 s71, v250, 26
	v_readlane_b32 s81, v250, 28
	s_mov_b32 s75, 0x11000
	s_movk_i32 s79, 0x60
	s_movk_i32 s64, 0x1000
	s_mov_b32 s72, 0x3f07dc22

	.amdhsa_kernel _Z11mega_kernel6Paramsii
		.amdhsa_group_segment_fixed_size 16640
		.amdhsa_private_segment_fixed_size 0
		.amdhsa_kernarg_size 488
		.amdhsa_user_sgpr_count 2
		.amdhsa_user_sgpr_dispatch_ptr 0
		.amdhsa_user_sgpr_queue_ptr 0
		.amdhsa_user_sgpr_kernarg_segment_ptr 1
		.amdhsa_user_sgpr_dispatch_id 0
		.amdhsa_user_sgpr_kernarg_preload_length 0
		.amdhsa_user_sgpr_kernarg_preload_offset 0
		.amdhsa_user_sgpr_private_segment_size 0
		.amdhsa_uses_dynamic_stack 0
		.amdhsa_enable_private_segment 0
		.amdhsa_system_sgpr_workgroup_id_x 1
		.amdhsa_system_sgpr_workgroup_id_y 0
		.amdhsa_system_sgpr_workgroup_id_z 0
		.amdhsa_system_sgpr_workgroup_info 0
		.amdhsa_system_vgpr_workitem_id 2
		.amdhsa_next_free_vgpr 256
		.amdhsa_next_free_sgpr 102
		.amdhsa_accum_offset 256
		.amdhsa_reserve_vcc 1
		.amdhsa_float_round_mode_32 0
		.amdhsa_float_round_mode_16_64 0
		.amdhsa_float_denorm_mode_32 3
		.amdhsa_float_denorm_mode_16_64 3
		.amdhsa_dx10_clamp 1
		.amdhsa_ieee_mode 1
		.amdhsa_fp16_overflow 0
		.amdhsa_tg_split 0
		.amdhsa_exception_fp_ieee_invalid_op 0
		.amdhsa_exception_fp_denorm_src 0
		.amdhsa_exception_fp_ieee_div_zero 0
		.amdhsa_exception_fp_ieee_overflow 0
		.amdhsa_exception_fp_ieee_underflow 0
		.amdhsa_exception_fp_ieee_inexact 0
		.amdhsa_exception_int_div_zero 0
	.end_amdhsa_kernel

amdhsa.kernels:
  - .agpr_count:     0
    .args:
      - .offset:         0
        .size:           224
        .value_kind:     by_value
      - .offset:         224
        .size:           4
        .value_kind:     by_value
      - .offset:         228
        .size:           4
        .value_kind:     by_value
      - .offset:         232
        .size:           4
        .value_kind:     hidden_block_count_x
      - .offset:         236
        .size:           4
        .value_kind:     hidden_block_count_y
      - .offset:         240
        .size:           4
        .value_kind:     hidden_block_count_z
      - .offset:         244
        .size:           2
        .value_kind:     hidden_group_size_x
      - .offset:         246
        .size:           2
        .value_kind:     hidden_group_size_y
      - .offset:         248
        .size:           2
        .value_kind:     hidden_group_size_z
      - .offset:         250
        .size:           2
        .value_kind:     hidden_remainder_x
      - .offset:         252
        .size:           2
        .value_kind:     hidden_remainder_y
      - .offset:         254
        .size:           2
        .value_kind:     hidden_remainder_z
      - .offset:         272
        .size:           8
        .value_kind:     hidden_global_offset_x
      - .offset:         280
        .size:           8
        .value_kind:     hidden_global_offset_y
      - .offset:         288
        .size:           8
        .value_kind:     hidden_global_offset_z
      - .offset:         296
        .size:           2
        .value_kind:     hidden_grid_dims
      - .offset:         320
        .size:           8
        .value_kind:     hidden_multigrid_sync_arg
      - .offset:         352
        .size:           4
        .value_kind:     hidden_dynamic_lds_size
    .group_segment_fixed_size: 16640
    .kernarg_segment_align: 8
    .kernarg_segment_size: 488
    .language:       OpenCL C
    .language_version:
      - 2
      - 0
    .max_flat_workgroup_size: 512
    .name:           _Z11mega_kernel6Paramsii
    .private_segment_fixed_size: 0
    .sgpr_count:     108
    .sgpr_spill_count: 197
    .symbol:         _Z11mega_kernel6Paramsii.kd
    .uniform_work_group_size: 1
    .uses_dynamic_stack: false
    .vgpr_count:     256
    .vgpr_spill_count: 0
    .wavefront_size: 64
